# GEMM K-loops: all s_setprio flips deleted (A/B of the role-split template's priority flips)
# speedup vs baseline: 1.0029x; 1.0029x over previous
.LBB0_120:
	ds_read_b128 v[130:133], v245
	ds_read_b128 v[134:137], v245 offset:1024
	ds_read_b128 v[138:141], v245 offset:2048
	ds_read_b128 v[142:145], v245 offset:3072
	s_waitcnt vmcnt(0)
	ds_read_b128 v[146:149], v246
	ds_read_b128 v[150:153], v246 offset:1024
	ds_read_b128 v[154:157], v246 offset:2048
	ds_read_b128 v[158:161], v246 offset:3072
	s_add_u32 s16, s6, 0xfffc0080
	s_addc_u32 s17, s7, -1
	s_cmp_eq_u32 s40, 12
	s_cselect_b32 s79, s1, s17
	s_cselect_b32 s78, s2, s16
	s_cselect_b32 s17, s3, s37
	s_cselect_b32 s16, s9, s35
	s_add_i32 m0, s71, 0xc000
	ds_read_b128 v[162:165], v247
	ds_read_b128 v[166:169], v247 offset:1024
	ds_read_b128 v[170:173], v247 offset:2048
	ds_read_b128 v[174:177], v247 offset:3072
	ds_read_b128 v[178:181], v247 offset:4096
	ds_read_b128 v[182:185], v247 offset:5120
	ds_read_b128 v[186:189], v247 offset:6144
	ds_read_b128 v[190:193], v247 offset:7168
	global_load_lds_dwordx4 v226, s[6:7]
	s_add_i32 m0, s71, 0xe000
	s_nop 0
	global_load_lds_dwordx4 v228, s[6:7]
	s_waitcnt vmcnt(8)
	s_waitcnt lgkmcnt(0)
	s_barrier
	s_waitcnt lgkmcnt(0)
	v_mfma_f32_16x16x32_bf16 v[126:129], v[130:133], v[162:165], v[126:129]
	v_mfma_f32_16x16x32_bf16 v[122:125], v[138:141], v[162:165], v[122:125]
	v_mfma_f32_16x16x32_bf16 v[110:113], v[130:133], v[170:173], v[110:113]
	v_mfma_f32_16x16x32_bf16 v[106:109], v[138:141], v[170:173], v[106:109]
	v_mfma_f32_16x16x32_bf16 v[94:97], v[130:133], v[178:181], v[94:97]
	v_mfma_f32_16x16x32_bf16 v[90:93], v[138:141], v[178:181], v[90:93]
	v_mfma_f32_16x16x32_bf16 v[78:81], v[130:133], v[186:189], v[78:81]
	v_mfma_f32_16x16x32_bf16 v[74:77], v[138:141], v[186:189], v[74:77]
	v_mfma_f32_16x16x32_bf16 v[126:129], v[134:137], v[166:169], v[126:129]
	v_mfma_f32_16x16x32_bf16 v[122:125], v[142:145], v[166:169], v[122:125]
	v_mfma_f32_16x16x32_bf16 v[110:113], v[134:137], v[174:177], v[110:113]
	v_mfma_f32_16x16x32_bf16 v[106:109], v[142:145], v[174:177], v[106:109]
	v_mfma_f32_16x16x32_bf16 v[94:97], v[134:137], v[182:185], v[94:97]
	v_mfma_f32_16x16x32_bf16 v[90:93], v[142:145], v[182:185], v[90:93]
	v_mfma_f32_16x16x32_bf16 v[78:81], v[134:137], v[190:193], v[78:81]
	v_mfma_f32_16x16x32_bf16 v[74:77], v[142:145], v[190:193], v[74:77]
	v_mfma_f32_16x16x32_bf16 v[118:121], v[146:149], v[162:165], v[118:121]
	v_mfma_f32_16x16x32_bf16 v[114:117], v[154:157], v[162:165], v[114:117]
	v_mfma_f32_16x16x32_bf16 v[102:105], v[146:149], v[170:173], v[102:105]
	v_mfma_f32_16x16x32_bf16 v[98:101], v[154:157], v[170:173], v[98:101]
	v_mfma_f32_16x16x32_bf16 v[86:89], v[146:149], v[178:181], v[86:89]
	v_mfma_f32_16x16x32_bf16 v[82:85], v[154:157], v[178:181], v[82:85]
	v_mfma_f32_16x16x32_bf16 v[70:73], v[146:149], v[186:189], v[70:73]
	v_mfma_f32_16x16x32_bf16 v[66:69], v[154:157], v[186:189], v[66:69]
	v_mfma_f32_16x16x32_bf16 v[118:121], v[150:153], v[166:169], v[118:121]
	v_mfma_f32_16x16x32_bf16 v[114:117], v[158:161], v[166:169], v[114:117]
	v_mfma_f32_16x16x32_bf16 v[102:105], v[150:153], v[174:177], v[102:105]
	v_mfma_f32_16x16x32_bf16 v[98:101], v[158:161], v[174:177], v[98:101]
	v_mfma_f32_16x16x32_bf16 v[86:89], v[150:153], v[182:185], v[86:89]
	v_mfma_f32_16x16x32_bf16 v[82:85], v[158:161], v[182:185], v[82:85]
	v_mfma_f32_16x16x32_bf16 v[70:73], v[150:153], v[190:193], v[70:73]
	v_mfma_f32_16x16x32_bf16 v[66:69], v[158:161], v[190:193], v[66:69]
	s_barrier
	s_add_i32 s41, s12, s39
	s_mov_b32 m0, s41
	ds_read_b128 v[162:165], v247 offset:16384
	ds_read_b128 v[166:169], v247 offset:17408
	ds_read_b128 v[170:173], v247 offset:18432
	ds_read_b128 v[174:177], v247 offset:19456
	ds_read_b128 v[178:181], v247 offset:20480
	ds_read_b128 v[182:185], v247 offset:21504
	ds_read_b128 v[186:189], v247 offset:22528
	ds_read_b128 v[190:193], v247 offset:23552
	global_load_lds_dwordx4 v212, s[16:17]
	s_add_i32 m0, s41, 0x2000
	s_add_u32 s42, s16, 0x40000
	s_addc_u32 s43, s17, 0
	s_add_i32 s41, s13, s39
	global_load_lds_dwordx4 v216, s[16:17]
	s_mov_b32 m0, s41
	s_nop 0
	global_load_lds_dwordx4 v212, s[42:43]
	s_add_i32 m0, s41, 0x2000
	s_nop 0
	global_load_lds_dwordx4 v216, s[42:43]
	s_mov_b32 m0, s71
	s_nop 0
	global_load_lds_dwordx4 v210, s[78:79]
	s_mov_b32 m0, s20
	s_nop 0
	global_load_lds_dwordx4 v214, s[78:79]
	s_waitcnt vmcnt(8)
	s_waitcnt lgkmcnt(0)
	s_barrier
	s_waitcnt lgkmcnt(0)
	v_mfma_f32_16x16x32_bf16 v[62:65], v[130:133], v[162:165], v[62:65]
	v_mfma_f32_16x16x32_bf16 v[58:61], v[138:141], v[162:165], v[58:61]
	v_mfma_f32_16x16x32_bf16 v[46:49], v[130:133], v[170:173], v[46:49]
	v_mfma_f32_16x16x32_bf16 v[42:45], v[138:141], v[170:173], v[42:45]
	v_mfma_f32_16x16x32_bf16 v[30:33], v[130:133], v[178:181], v[30:33]
	v_mfma_f32_16x16x32_bf16 v[26:29], v[138:141], v[178:181], v[26:29]
	v_mfma_f32_16x16x32_bf16 v[14:17], v[130:133], v[186:189], v[14:17]
	v_mfma_f32_16x16x32_bf16 v[10:13], v[138:141], v[186:189], v[10:13]
	v_mfma_f32_16x16x32_bf16 v[62:65], v[134:137], v[166:169], v[62:65]
	v_mfma_f32_16x16x32_bf16 v[58:61], v[142:145], v[166:169], v[58:61]
	v_mfma_f32_16x16x32_bf16 v[46:49], v[134:137], v[174:177], v[46:49]
	v_mfma_f32_16x16x32_bf16 v[42:45], v[142:145], v[174:177], v[42:45]
	v_mfma_f32_16x16x32_bf16 v[30:33], v[134:137], v[182:185], v[30:33]
	v_mfma_f32_16x16x32_bf16 v[26:29], v[142:145], v[182:185], v[26:29]
	v_mfma_f32_16x16x32_bf16 v[14:17], v[134:137], v[190:193], v[14:17]
	v_mfma_f32_16x16x32_bf16 v[10:13], v[142:145], v[190:193], v[10:13]
	v_mfma_f32_16x16x32_bf16 v[54:57], v[146:149], v[162:165], v[54:57]
	v_mfma_f32_16x16x32_bf16 v[50:53], v[154:157], v[162:165], v[50:53]
	v_mfma_f32_16x16x32_bf16 v[38:41], v[146:149], v[170:173], v[38:41]
	v_mfma_f32_16x16x32_bf16 v[34:37], v[154:157], v[170:173], v[34:37]
	v_mfma_f32_16x16x32_bf16 v[22:25], v[146:149], v[178:181], v[22:25]
	v_mfma_f32_16x16x32_bf16 v[18:21], v[154:157], v[178:181], v[18:21]
	v_mfma_f32_16x16x32_bf16 v[6:9], v[146:149], v[186:189], v[6:9]
	v_mfma_f32_16x16x32_bf16 v[2:5], v[154:157], v[186:189], v[2:5]
	v_mfma_f32_16x16x32_bf16 v[54:57], v[150:153], v[166:169], v[54:57]
	v_mfma_f32_16x16x32_bf16 v[50:53], v[158:161], v[166:169], v[50:53]
	v_mfma_f32_16x16x32_bf16 v[38:41], v[150:153], v[174:177], v[38:41]
	v_mfma_f32_16x16x32_bf16 v[34:37], v[158:161], v[174:177], v[34:37]
	v_mfma_f32_16x16x32_bf16 v[22:25], v[150:153], v[182:185], v[22:25]
	v_mfma_f32_16x16x32_bf16 v[18:21], v[158:161], v[182:185], v[18:21]
	v_mfma_f32_16x16x32_bf16 v[6:9], v[150:153], v[190:193], v[6:9]
	v_mfma_f32_16x16x32_bf16 v[2:5], v[158:161], v[190:193], v[2:5]
	s_barrier
	s_add_i32 s41, 0, 0x18000
	s_add_i32 s44, 0, 0x1c000
	v_add_u32_e32 v142, s41, v223
	v_add_u32_e32 v158, s44, v223
	ds_read_b128 v[130:133], v142
	ds_read_b128 v[134:137], v142 offset:1024
	ds_read_b128 v[138:141], v142 offset:2048
	ds_read_b128 v[142:145], v142 offset:3072
	ds_read_b128 v[146:149], v158
	ds_read_b128 v[150:153], v158 offset:1024
	ds_read_b128 v[154:157], v158 offset:2048
	ds_read_b128 v[158:161], v158 offset:3072
	s_add_u32 s42, s78, 0x40000
	s_addc_u32 s43, s79, 0
	s_mov_b32 m0, s21
	ds_read_b128 v[162:165], v247 offset:32768
	ds_read_b128 v[166:169], v247 offset:33792
	ds_read_b128 v[170:173], v247 offset:34816
	ds_read_b128 v[174:177], v247 offset:35840
	ds_read_b128 v[178:181], v247 offset:36864
	ds_read_b128 v[182:185], v247 offset:37888
	ds_read_b128 v[186:189], v247 offset:38912
	ds_read_b128 v[190:193], v247 offset:39936
	global_load_lds_dwordx4 v210, s[42:43]
	s_mov_b32 m0, s22
	s_nop 0
	global_load_lds_dwordx4 v214, s[42:43]
	s_waitcnt vmcnt(8)
	s_waitcnt lgkmcnt(0)
	s_barrier
	s_waitcnt lgkmcnt(0)
	v_mfma_f32_16x16x32_bf16 v[126:129], v[130:133], v[162:165], v[126:129]
	v_mfma_f32_16x16x32_bf16 v[122:125], v[138:141], v[162:165], v[122:125]
	v_mfma_f32_16x16x32_bf16 v[110:113], v[130:133], v[170:173], v[110:113]
	v_mfma_f32_16x16x32_bf16 v[106:109], v[138:141], v[170:173], v[106:109]
	v_mfma_f32_16x16x32_bf16 v[94:97], v[130:133], v[178:181], v[94:97]
	v_mfma_f32_16x16x32_bf16 v[90:93], v[138:141], v[178:181], v[90:93]
	v_mfma_f32_16x16x32_bf16 v[78:81], v[130:133], v[186:189], v[78:81]
	v_mfma_f32_16x16x32_bf16 v[74:77], v[138:141], v[186:189], v[74:77]
	v_mfma_f32_16x16x32_bf16 v[126:129], v[134:137], v[166:169], v[126:129]
	v_mfma_f32_16x16x32_bf16 v[122:125], v[142:145], v[166:169], v[122:125]
	v_mfma_f32_16x16x32_bf16 v[110:113], v[134:137], v[174:177], v[110:113]
	v_mfma_f32_16x16x32_bf16 v[106:109], v[142:145], v[174:177], v[106:109]
	v_mfma_f32_16x16x32_bf16 v[94:97], v[134:137], v[182:185], v[94:97]
	v_mfma_f32_16x16x32_bf16 v[90:93], v[142:145], v[182:185], v[90:93]
	v_mfma_f32_16x16x32_bf16 v[78:81], v[134:137], v[190:193], v[78:81]
	v_mfma_f32_16x16x32_bf16 v[74:77], v[142:145], v[190:193], v[74:77]
	v_mfma_f32_16x16x32_bf16 v[118:121], v[146:149], v[162:165], v[118:121]
	v_mfma_f32_16x16x32_bf16 v[114:117], v[154:157], v[162:165], v[114:117]
	v_mfma_f32_16x16x32_bf16 v[102:105], v[146:149], v[170:173], v[102:105]
	v_mfma_f32_16x16x32_bf16 v[98:101], v[154:157], v[170:173], v[98:101]
	v_mfma_f32_16x16x32_bf16 v[86:89], v[146:149], v[178:181], v[86:89]
	v_mfma_f32_16x16x32_bf16 v[82:85], v[154:157], v[178:181], v[82:85]
	v_mfma_f32_16x16x32_bf16 v[70:73], v[146:149], v[186:189], v[70:73]
	v_mfma_f32_16x16x32_bf16 v[66:69], v[154:157], v[186:189], v[66:69]
	v_mfma_f32_16x16x32_bf16 v[118:121], v[150:153], v[166:169], v[118:121]
	v_mfma_f32_16x16x32_bf16 v[114:117], v[158:161], v[166:169], v[114:117]
	v_mfma_f32_16x16x32_bf16 v[102:105], v[150:153], v[174:177], v[102:105]
	v_mfma_f32_16x16x32_bf16 v[98:101], v[158:161], v[174:177], v[98:101]
	v_mfma_f32_16x16x32_bf16 v[86:89], v[150:153], v[182:185], v[86:89]
	v_mfma_f32_16x16x32_bf16 v[82:85], v[158:161], v[182:185], v[82:85]
	v_mfma_f32_16x16x32_bf16 v[70:73], v[150:153], v[190:193], v[70:73]
	v_mfma_f32_16x16x32_bf16 v[66:69], v[158:161], v[190:193], v[66:69]
	s_barrier
	s_add_i32 s41, s41, s39
	s_add_i32 m0, s41, 0xffffff80
	ds_read_b128 v[162:165], v247 offset:49152
	ds_read_b128 v[166:169], v247 offset:50176
	ds_read_b128 v[170:173], v247 offset:51200
	ds_read_b128 v[174:177], v247 offset:52224
	ds_read_b128 v[178:181], v247 offset:53248
	ds_read_b128 v[182:185], v247 offset:54272
	ds_read_b128 v[186:189], v247 offset:55296
	ds_read_b128 v[190:193], v247 offset:56320
	global_load_lds_dwordx4 v212, s[16:17] offset:128
	s_add_i32 m0, s41, 0x1f80
	s_add_i32 s41, s44, s39
	global_load_lds_dwordx4 v216, s[16:17] offset:128
	s_add_u32 s16, s16, 0x40080
	s_addc_u32 s17, s17, 0
	s_mov_b32 m0, s41
	s_nop 0
	global_load_lds_dwordx4 v212, s[16:17]
	s_add_i32 m0, s41, 0x2000
	s_nop 0
	global_load_lds_dwordx4 v216, s[16:17]
	s_add_i32 m0, s14, 0xffffff80
	s_nop 0
	global_load_lds_dwordx4 v210, s[78:79] offset:128
	s_add_i32 m0, s15, 0xffffff80
	s_nop 0
	global_load_lds_dwordx4 v214, s[78:79] offset:128
	s_waitcnt vmcnt(8)
	s_waitcnt lgkmcnt(0)
	s_barrier
	s_waitcnt lgkmcnt(0)
	v_mfma_f32_16x16x32_bf16 v[62:65], v[130:133], v[162:165], v[62:65]
	v_mfma_f32_16x16x32_bf16 v[58:61], v[138:141], v[162:165], v[58:61]
	v_mfma_f32_16x16x32_bf16 v[46:49], v[130:133], v[170:173], v[46:49]
	v_mfma_f32_16x16x32_bf16 v[42:45], v[138:141], v[170:173], v[42:45]
	v_mfma_f32_16x16x32_bf16 v[30:33], v[130:133], v[178:181], v[30:33]
	v_mfma_f32_16x16x32_bf16 v[26:29], v[138:141], v[178:181], v[26:29]
	v_mfma_f32_16x16x32_bf16 v[14:17], v[130:133], v[186:189], v[14:17]
	v_mfma_f32_16x16x32_bf16 v[10:13], v[138:141], v[186:189], v[10:13]
	v_mfma_f32_16x16x32_bf16 v[62:65], v[134:137], v[166:169], v[62:65]
	v_mfma_f32_16x16x32_bf16 v[58:61], v[142:145], v[166:169], v[58:61]
	v_mfma_f32_16x16x32_bf16 v[46:49], v[134:137], v[174:177], v[46:49]
	v_mfma_f32_16x16x32_bf16 v[42:45], v[142:145], v[174:177], v[42:45]
	v_mfma_f32_16x16x32_bf16 v[30:33], v[134:137], v[182:185], v[30:33]
	v_mfma_f32_16x16x32_bf16 v[26:29], v[142:145], v[182:185], v[26:29]
	v_mfma_f32_16x16x32_bf16 v[14:17], v[134:137], v[190:193], v[14:17]
	v_mfma_f32_16x16x32_bf16 v[10:13], v[142:145], v[190:193], v[10:13]
	v_mfma_f32_16x16x32_bf16 v[54:57], v[146:149], v[162:165], v[54:57]
	v_mfma_f32_16x16x32_bf16 v[50:53], v[154:157], v[162:165], v[50:53]
	v_mfma_f32_16x16x32_bf16 v[38:41], v[146:149], v[170:173], v[38:41]
	v_mfma_f32_16x16x32_bf16 v[34:37], v[154:157], v[170:173], v[34:37]
	v_mfma_f32_16x16x32_bf16 v[22:25], v[146:149], v[178:181], v[22:25]
	v_mfma_f32_16x16x32_bf16 v[18:21], v[154:157], v[178:181], v[18:21]
	v_mfma_f32_16x16x32_bf16 v[6:9], v[146:149], v[186:189], v[6:9]
	v_mfma_f32_16x16x32_bf16 v[2:5], v[154:157], v[186:189], v[2:5]
	v_mfma_f32_16x16x32_bf16 v[54:57], v[150:153], v[166:169], v[54:57]
	v_mfma_f32_16x16x32_bf16 v[50:53], v[158:161], v[166:169], v[50:53]
	v_mfma_f32_16x16x32_bf16 v[38:41], v[150:153], v[174:177], v[38:41]
	v_mfma_f32_16x16x32_bf16 v[34:37], v[158:161], v[174:177], v[34:37]
	v_mfma_f32_16x16x32_bf16 v[22:25], v[150:153], v[182:185], v[22:25]
	v_mfma_f32_16x16x32_bf16 v[18:21], v[158:161], v[182:185], v[18:21]
	v_mfma_f32_16x16x32_bf16 v[6:9], v[150:153], v[190:193], v[6:9]
	v_mfma_f32_16x16x32_bf16 v[2:5], v[158:161], v[190:193], v[2:5]
	s_barrier
	s_add_i32 s40, s40, 2
	s_add_u32 s6, s6, 0x100
	s_addc_u32 s7, s7, 0
	s_add_u32 s35, s35, 0x100
	s_addc_u32 s37, s37, 0
	s_cmp_gt_u32 s40, 13
	s_cbranch_scc0 .LBB0_120
	s_and_b64 vcc, exec, s[48:49]
	s_cbranch_vccz .LBB0_123
	s_barrier

.LBB0_518:
	ds_read_b128 v[148:151], v143
	ds_read_b128 v[152:155], v143 offset:1024
	ds_read_b128 v[158:161], v143 offset:2048
	ds_read_b128 v[162:165], v143 offset:3072
	ds_read_b128 v[166:169], v144
	ds_read_b128 v[170:173], v144 offset:1024
	ds_read_b128 v[174:177], v144 offset:2048
	ds_read_b128 v[178:181], v144 offset:3072
	s_add_u32 s16, s8, s10
	s_addc_u32 s17, s9, s11
	s_add_u32 s16, s16, 0x1000100
	s_addc_u32 s17, s17, 0
	s_add_u32 s44, s30, s10
	s_addc_u32 s45, s31, s11
	s_cmpk_eq_i32 s10, 0x700
	s_cselect_b32 s29, s7, s17
	s_cselect_b32 s28, s6, s16
	s_cselect_b32 s17, s5, s45
	s_cselect_b32 s16, s4, s44
	s_mov_b32 m0, s34
	v_lshl_add_u64 v[214:215], v[138:139], 0, s[10:11]
	ds_read_b128 v[182:185], v145
	ds_read_b128 v[186:189], v145 offset:1024
	ds_read_b128 v[190:193], v145 offset:2048
	ds_read_b128 v[194:197], v145 offset:3072
	ds_read_b128 v[198:201], v145 offset:4096
	ds_read_b128 v[202:205], v145 offset:5120
	ds_read_b128 v[206:209], v145 offset:6144
	ds_read_b128 v[210:213], v145 offset:7168
	global_load_lds_dwordx4 v[214:215], off
	v_lshl_add_u64 v[214:215], v[140:141], 0, s[10:11]
	s_mov_b32 m0, s35
	s_nop 0
	global_load_lds_dwordx4 v[214:215], off
	s_waitcnt vmcnt(8)
	s_waitcnt lgkmcnt(0)
	s_barrier
	s_waitcnt lgkmcnt(0)
	v_mfma_f32_16x16x32_bf16 v[126:129], v[148:151], v[182:185], v[126:129]
	v_mfma_f32_16x16x32_bf16 v[122:125], v[158:161], v[182:185], v[122:125]
	v_mfma_f32_16x16x32_bf16 v[110:113], v[148:151], v[190:193], v[110:113]
	v_mfma_f32_16x16x32_bf16 v[106:109], v[158:161], v[190:193], v[106:109]
	v_mfma_f32_16x16x32_bf16 v[94:97], v[148:151], v[198:201], v[94:97]
	v_mfma_f32_16x16x32_bf16 v[90:93], v[158:161], v[198:201], v[90:93]
	v_mfma_f32_16x16x32_bf16 v[78:81], v[148:151], v[206:209], v[78:81]
	v_mfma_f32_16x16x32_bf16 v[74:77], v[158:161], v[206:209], v[74:77]
	v_mfma_f32_16x16x32_bf16 v[126:129], v[152:155], v[186:189], v[126:129]
	v_mfma_f32_16x16x32_bf16 v[122:125], v[162:165], v[186:189], v[122:125]
	v_mfma_f32_16x16x32_bf16 v[110:113], v[152:155], v[194:197], v[110:113]
	v_mfma_f32_16x16x32_bf16 v[106:109], v[162:165], v[194:197], v[106:109]
	v_mfma_f32_16x16x32_bf16 v[94:97], v[152:155], v[202:205], v[94:97]
	v_mfma_f32_16x16x32_bf16 v[90:93], v[162:165], v[202:205], v[90:93]
	v_mfma_f32_16x16x32_bf16 v[78:81], v[152:155], v[210:213], v[78:81]
	v_mfma_f32_16x16x32_bf16 v[74:77], v[162:165], v[210:213], v[74:77]
	v_mfma_f32_16x16x32_bf16 v[118:121], v[166:169], v[182:185], v[118:121]
	v_mfma_f32_16x16x32_bf16 v[114:117], v[174:177], v[182:185], v[114:117]
	v_mfma_f32_16x16x32_bf16 v[102:105], v[166:169], v[190:193], v[102:105]
	v_mfma_f32_16x16x32_bf16 v[98:101], v[174:177], v[190:193], v[98:101]
	v_mfma_f32_16x16x32_bf16 v[86:89], v[166:169], v[198:201], v[86:89]
	v_mfma_f32_16x16x32_bf16 v[82:85], v[174:177], v[198:201], v[82:85]
	v_mfma_f32_16x16x32_bf16 v[70:73], v[166:169], v[206:209], v[70:73]
	v_mfma_f32_16x16x32_bf16 v[66:69], v[174:177], v[206:209], v[66:69]
	v_mfma_f32_16x16x32_bf16 v[118:121], v[170:173], v[186:189], v[118:121]
	v_mfma_f32_16x16x32_bf16 v[114:117], v[178:181], v[186:189], v[114:117]
	v_mfma_f32_16x16x32_bf16 v[102:105], v[170:173], v[194:197], v[102:105]
	v_mfma_f32_16x16x32_bf16 v[98:101], v[178:181], v[194:197], v[98:101]
	v_mfma_f32_16x16x32_bf16 v[86:89], v[170:173], v[202:205], v[86:89]
	v_mfma_f32_16x16x32_bf16 v[82:85], v[178:181], v[202:205], v[82:85]
	v_mfma_f32_16x16x32_bf16 v[70:73], v[170:173], v[210:213], v[70:73]
	v_mfma_f32_16x16x32_bf16 v[66:69], v[178:181], v[210:213], v[66:69]
	s_barrier
	s_mov_b32 m0, s36
	v_lshl_add_u64 v[214:215], s[16:17], 0, v[132:133]
	s_add_u32 s44, s16, 0x40000
	ds_read_b128 v[182:185], v145 offset:16384
	ds_read_b128 v[186:189], v145 offset:17408
	ds_read_b128 v[190:193], v145 offset:18432
	ds_read_b128 v[194:197], v145 offset:19456
	ds_read_b128 v[198:201], v145 offset:20480
	ds_read_b128 v[202:205], v145 offset:21504
	ds_read_b128 v[206:209], v145 offset:22528
	ds_read_b128 v[210:213], v145 offset:23552
	global_load_lds_dwordx4 v132, s[16:17]
	v_lshl_add_u64 v[216:217], s[16:17], 0, v[136:137]
	s_mov_b32 m0, s37
	s_addc_u32 s45, s17, 0
	global_load_lds_dwordx4 v136, s[16:17]
	s_mov_b32 m0, s38
	v_lshl_add_u64 v[220:221], s[28:29], 0, v[134:135]
	global_load_lds_dwordx4 v132, s[44:45]
	s_mov_b32 m0, s39
	s_nop 0
	global_load_lds_dwordx4 v136, s[44:45]
	v_lshl_add_u64 v[218:219], s[28:29], 0, v[130:131]
	s_mov_b32 m0, s1
	s_nop 0
	global_load_lds_dwordx4 v130, s[28:29]
	s_mov_b32 m0, s15
	s_nop 0
	global_load_lds_dwordx4 v134, s[28:29]
	s_waitcnt vmcnt(8)
	s_waitcnt lgkmcnt(0)
	s_barrier
	s_waitcnt lgkmcnt(0)
	v_mfma_f32_16x16x32_bf16 v[62:65], v[148:151], v[182:185], v[62:65]
	v_mfma_f32_16x16x32_bf16 v[58:61], v[158:161], v[182:185], v[58:61]
	v_mfma_f32_16x16x32_bf16 v[46:49], v[148:151], v[190:193], v[46:49]
	v_mfma_f32_16x16x32_bf16 v[42:45], v[158:161], v[190:193], v[42:45]
	v_mfma_f32_16x16x32_bf16 v[30:33], v[148:151], v[198:201], v[30:33]
	v_mfma_f32_16x16x32_bf16 v[26:29], v[158:161], v[198:201], v[26:29]
	v_mfma_f32_16x16x32_bf16 v[14:17], v[148:151], v[206:209], v[14:17]
	v_mfma_f32_16x16x32_bf16 v[10:13], v[158:161], v[206:209], v[10:13]
	v_mfma_f32_16x16x32_bf16 v[62:65], v[152:155], v[186:189], v[62:65]
	v_mfma_f32_16x16x32_bf16 v[58:61], v[162:165], v[186:189], v[58:61]
	v_mfma_f32_16x16x32_bf16 v[46:49], v[152:155], v[194:197], v[46:49]
	v_mfma_f32_16x16x32_bf16 v[42:45], v[162:165], v[194:197], v[42:45]
	v_mfma_f32_16x16x32_bf16 v[30:33], v[152:155], v[202:205], v[30:33]
	v_mfma_f32_16x16x32_bf16 v[26:29], v[162:165], v[202:205], v[26:29]
	v_mfma_f32_16x16x32_bf16 v[14:17], v[152:155], v[210:213], v[14:17]
	v_mfma_f32_16x16x32_bf16 v[10:13], v[162:165], v[210:213], v[10:13]
	v_mfma_f32_16x16x32_bf16 v[54:57], v[166:169], v[182:185], v[54:57]
	v_mfma_f32_16x16x32_bf16 v[50:53], v[174:177], v[182:185], v[50:53]
	v_mfma_f32_16x16x32_bf16 v[38:41], v[166:169], v[190:193], v[38:41]
	v_mfma_f32_16x16x32_bf16 v[34:37], v[174:177], v[190:193], v[34:37]
	v_mfma_f32_16x16x32_bf16 v[22:25], v[166:169], v[198:201], v[22:25]
	v_mfma_f32_16x16x32_bf16 v[18:21], v[174:177], v[198:201], v[18:21]
	v_mfma_f32_16x16x32_bf16 v[6:9], v[166:169], v[206:209], v[6:9]
	v_mfma_f32_16x16x32_bf16 v[2:5], v[174:177], v[206:209], v[2:5]
	v_mfma_f32_16x16x32_bf16 v[54:57], v[170:173], v[186:189], v[54:57]
	v_mfma_f32_16x16x32_bf16 v[50:53], v[178:181], v[186:189], v[50:53]
	v_mfma_f32_16x16x32_bf16 v[38:41], v[170:173], v[194:197], v[38:41]
	v_mfma_f32_16x16x32_bf16 v[34:37], v[178:181], v[194:197], v[34:37]
	v_mfma_f32_16x16x32_bf16 v[22:25], v[170:173], v[202:205], v[22:25]
	v_mfma_f32_16x16x32_bf16 v[18:21], v[178:181], v[202:205], v[18:21]
	v_mfma_f32_16x16x32_bf16 v[6:9], v[170:173], v[210:213], v[6:9]
	v_mfma_f32_16x16x32_bf16 v[2:5], v[178:181], v[210:213], v[2:5]
	s_barrier
	ds_read_b128 v[148:151], v146
	ds_read_b128 v[152:155], v146 offset:1024
	ds_read_b128 v[158:161], v146 offset:2048
	ds_read_b128 v[162:165], v146 offset:3072
	ds_read_b128 v[166:169], v147
	ds_read_b128 v[170:173], v147 offset:1024
	ds_read_b128 v[174:177], v147 offset:2048
	ds_read_b128 v[178:181], v147 offset:3072
	s_add_u32 s28, s28, 0x40000
	s_addc_u32 s29, s29, 0
	s_mov_b32 m0, s20
	ds_read_b128 v[182:185], v145 offset:32768
	ds_read_b128 v[186:189], v145 offset:33792
	ds_read_b128 v[190:193], v145 offset:34816
	ds_read_b128 v[194:197], v145 offset:35840
	ds_read_b128 v[198:201], v145 offset:36864
	ds_read_b128 v[202:205], v145 offset:37888
	ds_read_b128 v[206:209], v145 offset:38912
	ds_read_b128 v[210:213], v145 offset:39936
	global_load_lds_dwordx4 v130, s[28:29]
	s_mov_b32 m0, s21
	s_nop 0
	global_load_lds_dwordx4 v134, s[28:29]
	s_waitcnt vmcnt(8)
	s_waitcnt lgkmcnt(0)
	s_barrier
	s_waitcnt lgkmcnt(0)
	v_mfma_f32_16x16x32_bf16 v[126:129], v[148:151], v[182:185], v[126:129]
	v_mfma_f32_16x16x32_bf16 v[122:125], v[158:161], v[182:185], v[122:125]
	v_mfma_f32_16x16x32_bf16 v[110:113], v[148:151], v[190:193], v[110:113]
	v_mfma_f32_16x16x32_bf16 v[106:109], v[158:161], v[190:193], v[106:109]
	v_mfma_f32_16x16x32_bf16 v[94:97], v[148:151], v[198:201], v[94:97]
	v_mfma_f32_16x16x32_bf16 v[90:93], v[158:161], v[198:201], v[90:93]
	v_mfma_f32_16x16x32_bf16 v[78:81], v[148:151], v[206:209], v[78:81]
	v_mfma_f32_16x16x32_bf16 v[74:77], v[158:161], v[206:209], v[74:77]
	v_mfma_f32_16x16x32_bf16 v[126:129], v[152:155], v[186:189], v[126:129]
	v_mfma_f32_16x16x32_bf16 v[122:125], v[162:165], v[186:189], v[122:125]
	v_mfma_f32_16x16x32_bf16 v[110:113], v[152:155], v[194:197], v[110:113]
	v_mfma_f32_16x16x32_bf16 v[106:109], v[162:165], v[194:197], v[106:109]
	v_mfma_f32_16x16x32_bf16 v[94:97], v[152:155], v[202:205], v[94:97]
	v_mfma_f32_16x16x32_bf16 v[90:93], v[162:165], v[202:205], v[90:93]
	v_mfma_f32_16x16x32_bf16 v[78:81], v[152:155], v[210:213], v[78:81]
	v_mfma_f32_16x16x32_bf16 v[74:77], v[162:165], v[210:213], v[74:77]
	v_mfma_f32_16x16x32_bf16 v[118:121], v[166:169], v[182:185], v[118:121]
	v_mfma_f32_16x16x32_bf16 v[114:117], v[174:177], v[182:185], v[114:117]
	v_mfma_f32_16x16x32_bf16 v[102:105], v[166:169], v[190:193], v[102:105]
	v_mfma_f32_16x16x32_bf16 v[98:101], v[174:177], v[190:193], v[98:101]
	v_mfma_f32_16x16x32_bf16 v[86:89], v[166:169], v[198:201], v[86:89]
	v_mfma_f32_16x16x32_bf16 v[82:85], v[174:177], v[198:201], v[82:85]
	v_mfma_f32_16x16x32_bf16 v[70:73], v[166:169], v[206:209], v[70:73]
	v_mfma_f32_16x16x32_bf16 v[66:69], v[174:177], v[206:209], v[66:69]
	v_mfma_f32_16x16x32_bf16 v[118:121], v[170:173], v[186:189], v[118:121]
	v_mfma_f32_16x16x32_bf16 v[114:117], v[178:181], v[186:189], v[114:117]
	v_mfma_f32_16x16x32_bf16 v[102:105], v[170:173], v[194:197], v[102:105]
	v_mfma_f32_16x16x32_bf16 v[98:101], v[178:181], v[194:197], v[98:101]
	v_mfma_f32_16x16x32_bf16 v[86:89], v[170:173], v[202:205], v[86:89]
	v_mfma_f32_16x16x32_bf16 v[82:85], v[178:181], v[202:205], v[82:85]
	v_mfma_f32_16x16x32_bf16 v[70:73], v[170:173], v[210:213], v[70:73]
	v_mfma_f32_16x16x32_bf16 v[66:69], v[178:181], v[210:213], v[66:69]
	s_barrier
	s_mov_b32 m0, s40
	v_lshl_add_u64 v[214:215], v[214:215], 0, s[2:3]
	s_add_u32 s16, s16, 0x40080
	ds_read_b128 v[182:185], v145 offset:49152
	ds_read_b128 v[186:189], v145 offset:50176
	ds_read_b128 v[190:193], v145 offset:51200
	ds_read_b128 v[194:197], v145 offset:52224
	ds_read_b128 v[198:201], v145 offset:53248
	ds_read_b128 v[202:205], v145 offset:54272
	ds_read_b128 v[206:209], v145 offset:55296
	ds_read_b128 v[210:213], v145 offset:56320
	global_load_lds_dwordx4 v[214:215], off
	v_lshl_add_u64 v[214:215], v[216:217], 0, s[2:3]
	s_mov_b32 m0, s41
	s_addc_u32 s17, s17, 0
	global_load_lds_dwordx4 v[214:215], off
	s_mov_b32 m0, s42
	s_nop 0
	global_load_lds_dwordx4 v132, s[16:17]
	s_mov_b32 m0, s43
	s_nop 0
	global_load_lds_dwordx4 v136, s[16:17]
	v_lshl_add_u64 v[214:215], v[218:219], 0, s[2:3]
	s_mov_b32 m0, s22
	s_nop 0
	global_load_lds_dwordx4 v[214:215], off
	v_lshl_add_u64 v[214:215], v[220:221], 0, s[2:3]
	s_mov_b32 m0, s23
	s_nop 0
	global_load_lds_dwordx4 v[214:215], off
	s_waitcnt vmcnt(8)
	s_waitcnt lgkmcnt(0)
	s_barrier
	s_waitcnt lgkmcnt(0)
	v_mfma_f32_16x16x32_bf16 v[62:65], v[148:151], v[182:185], v[62:65]
	v_mfma_f32_16x16x32_bf16 v[58:61], v[158:161], v[182:185], v[58:61]
	v_mfma_f32_16x16x32_bf16 v[46:49], v[148:151], v[190:193], v[46:49]
	v_mfma_f32_16x16x32_bf16 v[42:45], v[158:161], v[190:193], v[42:45]
	v_mfma_f32_16x16x32_bf16 v[30:33], v[148:151], v[198:201], v[30:33]
	v_mfma_f32_16x16x32_bf16 v[26:29], v[158:161], v[198:201], v[26:29]
	v_mfma_f32_16x16x32_bf16 v[14:17], v[148:151], v[206:209], v[14:17]
	v_mfma_f32_16x16x32_bf16 v[10:13], v[158:161], v[206:209], v[10:13]
	v_mfma_f32_16x16x32_bf16 v[62:65], v[152:155], v[186:189], v[62:65]
	v_mfma_f32_16x16x32_bf16 v[58:61], v[162:165], v[186:189], v[58:61]
	v_mfma_f32_16x16x32_bf16 v[46:49], v[152:155], v[194:197], v[46:49]
	v_mfma_f32_16x16x32_bf16 v[42:45], v[162:165], v[194:197], v[42:45]
	v_mfma_f32_16x16x32_bf16 v[30:33], v[152:155], v[202:205], v[30:33]
	v_mfma_f32_16x16x32_bf16 v[26:29], v[162:165], v[202:205], v[26:29]
	v_mfma_f32_16x16x32_bf16 v[14:17], v[152:155], v[210:213], v[14:17]
	v_mfma_f32_16x16x32_bf16 v[10:13], v[162:165], v[210:213], v[10:13]
	v_mfma_f32_16x16x32_bf16 v[54:57], v[166:169], v[182:185], v[54:57]
	v_mfma_f32_16x16x32_bf16 v[50:53], v[174:177], v[182:185], v[50:53]
	v_mfma_f32_16x16x32_bf16 v[38:41], v[166:169], v[190:193], v[38:41]
	v_mfma_f32_16x16x32_bf16 v[34:37], v[174:177], v[190:193], v[34:37]
	v_mfma_f32_16x16x32_bf16 v[22:25], v[166:169], v[198:201], v[22:25]
	v_mfma_f32_16x16x32_bf16 v[18:21], v[174:177], v[198:201], v[18:21]
	v_mfma_f32_16x16x32_bf16 v[6:9], v[166:169], v[206:209], v[6:9]
	v_mfma_f32_16x16x32_bf16 v[2:5], v[174:177], v[206:209], v[2:5]
	v_mfma_f32_16x16x32_bf16 v[54:57], v[170:173], v[186:189], v[54:57]
	v_mfma_f32_16x16x32_bf16 v[50:53], v[178:181], v[186:189], v[50:53]
	v_mfma_f32_16x16x32_bf16 v[38:41], v[170:173], v[194:197], v[38:41]
	v_mfma_f32_16x16x32_bf16 v[34:37], v[178:181], v[194:197], v[34:37]
	v_mfma_f32_16x16x32_bf16 v[22:25], v[170:173], v[202:205], v[22:25]
	v_mfma_f32_16x16x32_bf16 v[18:21], v[178:181], v[202:205], v[18:21]
	v_mfma_f32_16x16x32_bf16 v[6:9], v[170:173], v[210:213], v[6:9]
	v_mfma_f32_16x16x32_bf16 v[2:5], v[178:181], v[210:213], v[2:5]
	s_barrier
	s_add_i32 s33, s33, 2
	s_add_u32 s10, s10, 0x100
	s_addc_u32 s11, s11, 0
	s_cmp_gt_u32 s33, 13
	s_cbranch_scc0 .LBB0_518
	s_cmpk_lt_u32 s14, 0x100
	s_cbranch_scc0 .LBB0_521
	s_barrier

.LBB0_1250:
	ds_read_b128 v[146:149], v140
	ds_read_b128 v[150:153], v140 offset:1024
	ds_read_b128 v[154:157], v140 offset:2048
	ds_read_b128 v[158:161], v140 offset:3072
	ds_read_b128 v[162:165], v141
	ds_read_b128 v[166:169], v141 offset:1024
	ds_read_b128 v[170:173], v141 offset:2048
	ds_read_b128 v[174:177], v141 offset:3072
	s_add_u32 s14, s10, s12
	s_addc_u32 s15, s11, s13
	s_add_u32 s14, s14, 0x11400100
	s_addc_u32 s15, s15, 0
	s_add_u32 s39, s1, s12
	s_addc_u32 s40, s26, s13
	s_cmpk_eq_i32 s12, 0x700
	s_cselect_b32 s17, s9, s15
	s_cselect_b32 s16, s8, s14
	s_cselect_b32 s15, s7, s40
	s_cselect_b32 s14, s6, s39
	s_mov_b32 m0, s28
	v_lshl_add_u64 v[210:211], v[134:135], 0, s[12:13]
	ds_read_b128 v[178:181], v142
	ds_read_b128 v[182:185], v142 offset:1024
	ds_read_b128 v[186:189], v142 offset:2048
	ds_read_b128 v[190:193], v142 offset:3072
	ds_read_b128 v[194:197], v142 offset:4096
	ds_read_b128 v[198:201], v142 offset:5120
	ds_read_b128 v[202:205], v142 offset:6144
	ds_read_b128 v[206:209], v142 offset:7168
	global_load_lds_dwordx4 v[210:211], off
	v_lshl_add_u64 v[210:211], v[136:137], 0, s[12:13]
	s_mov_b32 m0, s29
	s_nop 0
	global_load_lds_dwordx4 v[210:211], off
	s_waitcnt vmcnt(8)
	s_waitcnt lgkmcnt(0)
	s_barrier
	s_waitcnt lgkmcnt(0)
	v_mfma_f32_16x16x32_bf16 v[126:129], v[146:149], v[178:181], v[126:129]
	v_mfma_f32_16x16x32_bf16 v[122:125], v[154:157], v[178:181], v[122:125]
	v_mfma_f32_16x16x32_bf16 v[118:121], v[146:149], v[186:189], v[118:121]
	v_mfma_f32_16x16x32_bf16 v[114:117], v[154:157], v[186:189], v[114:117]
	v_mfma_f32_16x16x32_bf16 v[106:109], v[146:149], v[194:197], v[106:109]
	v_mfma_f32_16x16x32_bf16 v[98:101], v[154:157], v[194:197], v[98:101]
	v_mfma_f32_16x16x32_bf16 v[82:85], v[146:149], v[202:205], v[82:85]
	v_mfma_f32_16x16x32_bf16 v[74:77], v[154:157], v[202:205], v[74:77]
	v_mfma_f32_16x16x32_bf16 v[126:129], v[150:153], v[182:185], v[126:129]
	v_mfma_f32_16x16x32_bf16 v[122:125], v[158:161], v[182:185], v[122:125]
	v_mfma_f32_16x16x32_bf16 v[118:121], v[150:153], v[190:193], v[118:121]
	v_mfma_f32_16x16x32_bf16 v[114:117], v[158:161], v[190:193], v[114:117]
	v_mfma_f32_16x16x32_bf16 v[106:109], v[150:153], v[198:201], v[106:109]
	v_mfma_f32_16x16x32_bf16 v[98:101], v[158:161], v[198:201], v[98:101]
	v_mfma_f32_16x16x32_bf16 v[82:85], v[150:153], v[206:209], v[82:85]
	v_mfma_f32_16x16x32_bf16 v[74:77], v[158:161], v[206:209], v[74:77]
	v_mfma_f32_16x16x32_bf16 v[110:113], v[162:165], v[178:181], v[110:113]
	v_mfma_f32_16x16x32_bf16 v[102:105], v[170:173], v[178:181], v[102:105]
	v_mfma_f32_16x16x32_bf16 v[94:97], v[162:165], v[186:189], v[94:97]
	v_mfma_f32_16x16x32_bf16 v[90:93], v[170:173], v[186:189], v[90:93]
	v_mfma_f32_16x16x32_bf16 v[86:89], v[162:165], v[194:197], v[86:89]
	v_mfma_f32_16x16x32_bf16 v[78:81], v[170:173], v[194:197], v[78:81]
	v_mfma_f32_16x16x32_bf16 v[70:73], v[162:165], v[202:205], v[70:73]
	v_mfma_f32_16x16x32_bf16 v[66:69], v[170:173], v[202:205], v[66:69]
	v_mfma_f32_16x16x32_bf16 v[110:113], v[166:169], v[182:185], v[110:113]
	v_mfma_f32_16x16x32_bf16 v[102:105], v[174:177], v[182:185], v[102:105]
	v_mfma_f32_16x16x32_bf16 v[94:97], v[166:169], v[190:193], v[94:97]
	v_mfma_f32_16x16x32_bf16 v[90:93], v[174:177], v[190:193], v[90:93]
	v_mfma_f32_16x16x32_bf16 v[86:89], v[166:169], v[198:201], v[86:89]
	v_mfma_f32_16x16x32_bf16 v[78:81], v[174:177], v[198:201], v[78:81]
	v_mfma_f32_16x16x32_bf16 v[70:73], v[166:169], v[206:209], v[70:73]
	v_mfma_f32_16x16x32_bf16 v[66:69], v[174:177], v[206:209], v[66:69]
	s_barrier
	s_mov_b32 m0, s30
	v_lshl_add_u64 v[210:211], s[14:15], 0, v[130:131]
	s_add_u32 s40, s14, 0x40000
	ds_read_b128 v[178:181], v142 offset:16384
	ds_read_b128 v[182:185], v142 offset:17408
	ds_read_b128 v[186:189], v142 offset:18432
	ds_read_b128 v[190:193], v142 offset:19456
	ds_read_b128 v[194:197], v142 offset:20480
	ds_read_b128 v[198:201], v142 offset:21504
	ds_read_b128 v[202:205], v142 offset:22528
	ds_read_b128 v[206:209], v142 offset:23552
	global_load_lds_dwordx4 v130, s[14:15]
	v_lshl_add_u64 v[212:213], s[14:15], 0, v[132:133]
	s_mov_b32 m0, s31
	s_addc_u32 s41, s15, 0
	global_load_lds_dwordx4 v132, s[14:15]
	s_mov_b32 m0, s33
	v_lshl_add_u64 v[216:217], s[16:17], 0, v[132:133]
	global_load_lds_dwordx4 v130, s[40:41]
	s_mov_b32 m0, s34
	s_nop 0
	global_load_lds_dwordx4 v132, s[40:41]
	v_lshl_add_u64 v[214:215], s[16:17], 0, v[130:131]
	s_mov_b32 m0, s5
	s_nop 0
	global_load_lds_dwordx4 v130, s[16:17]
	s_mov_b32 m0, s21
	s_nop 0
	global_load_lds_dwordx4 v132, s[16:17]
	s_waitcnt vmcnt(8)
	s_waitcnt lgkmcnt(0)
	s_barrier
	s_waitcnt lgkmcnt(0)
	v_mfma_f32_16x16x32_bf16 v[62:65], v[146:149], v[178:181], v[62:65]
	v_mfma_f32_16x16x32_bf16 v[58:61], v[154:157], v[178:181], v[58:61]
	v_mfma_f32_16x16x32_bf16 v[54:57], v[146:149], v[186:189], v[54:57]
	v_mfma_f32_16x16x32_bf16 v[50:53], v[154:157], v[186:189], v[50:53]
	v_mfma_f32_16x16x32_bf16 v[34:37], v[146:149], v[194:197], v[34:37]
	v_mfma_f32_16x16x32_bf16 v[26:29], v[154:157], v[194:197], v[26:29]
	v_mfma_f32_16x16x32_bf16 v[22:25], v[146:149], v[202:205], v[22:25]
	v_mfma_f32_16x16x32_bf16 v[10:13], v[154:157], v[202:205], v[10:13]
	v_mfma_f32_16x16x32_bf16 v[62:65], v[150:153], v[182:185], v[62:65]
	v_mfma_f32_16x16x32_bf16 v[58:61], v[158:161], v[182:185], v[58:61]
	v_mfma_f32_16x16x32_bf16 v[54:57], v[150:153], v[190:193], v[54:57]
	v_mfma_f32_16x16x32_bf16 v[50:53], v[158:161], v[190:193], v[50:53]
	v_mfma_f32_16x16x32_bf16 v[34:37], v[150:153], v[198:201], v[34:37]
	v_mfma_f32_16x16x32_bf16 v[26:29], v[158:161], v[198:201], v[26:29]
	v_mfma_f32_16x16x32_bf16 v[22:25], v[150:153], v[206:209], v[22:25]
	v_mfma_f32_16x16x32_bf16 v[10:13], v[158:161], v[206:209], v[10:13]
	v_mfma_f32_16x16x32_bf16 v[46:49], v[162:165], v[178:181], v[46:49]
	v_mfma_f32_16x16x32_bf16 v[42:45], v[170:173], v[178:181], v[42:45]
	v_mfma_f32_16x16x32_bf16 v[38:41], v[162:165], v[186:189], v[38:41]
	v_mfma_f32_16x16x32_bf16 v[30:33], v[170:173], v[186:189], v[30:33]
	v_mfma_f32_16x16x32_bf16 v[18:21], v[162:165], v[194:197], v[18:21]
	v_mfma_f32_16x16x32_bf16 v[14:17], v[170:173], v[194:197], v[14:17]
	v_mfma_f32_16x16x32_bf16 v[6:9], v[162:165], v[202:205], v[6:9]
	v_mfma_f32_16x16x32_bf16 v[2:5], v[170:173], v[202:205], v[2:5]
	v_mfma_f32_16x16x32_bf16 v[46:49], v[166:169], v[182:185], v[46:49]
	v_mfma_f32_16x16x32_bf16 v[42:45], v[174:177], v[182:185], v[42:45]
	v_mfma_f32_16x16x32_bf16 v[38:41], v[166:169], v[190:193], v[38:41]
	v_mfma_f32_16x16x32_bf16 v[30:33], v[174:177], v[190:193], v[30:33]
	v_mfma_f32_16x16x32_bf16 v[18:21], v[166:169], v[198:201], v[18:21]
	v_mfma_f32_16x16x32_bf16 v[14:17], v[174:177], v[198:201], v[14:17]
	v_mfma_f32_16x16x32_bf16 v[6:9], v[166:169], v[206:209], v[6:9]
	v_mfma_f32_16x16x32_bf16 v[2:5], v[174:177], v[206:209], v[2:5]
	s_barrier
	ds_read_b128 v[146:149], v143
	ds_read_b128 v[150:153], v143 offset:1024
	ds_read_b128 v[154:157], v143 offset:2048
	ds_read_b128 v[158:161], v143 offset:3072
	ds_read_b128 v[162:165], v144
	ds_read_b128 v[166:169], v144 offset:1024
	ds_read_b128 v[170:173], v144 offset:2048
	ds_read_b128 v[174:177], v144 offset:3072
	s_add_u32 s16, s16, 0x40000
	s_addc_u32 s17, s17, 0
	s_mov_b32 m0, s22
	ds_read_b128 v[178:181], v142 offset:32768
	ds_read_b128 v[182:185], v142 offset:33792
	ds_read_b128 v[186:189], v142 offset:34816
	ds_read_b128 v[190:193], v142 offset:35840
	ds_read_b128 v[194:197], v142 offset:36864
	ds_read_b128 v[198:201], v142 offset:37888
	ds_read_b128 v[202:205], v142 offset:38912
	ds_read_b128 v[206:209], v142 offset:39936
	global_load_lds_dwordx4 v130, s[16:17]
	s_mov_b32 m0, s23
	s_nop 0
	global_load_lds_dwordx4 v132, s[16:17]
	s_waitcnt vmcnt(8)
	s_waitcnt lgkmcnt(0)
	s_barrier
	s_waitcnt lgkmcnt(0)
	v_mfma_f32_16x16x32_bf16 v[126:129], v[146:149], v[178:181], v[126:129]
	v_mfma_f32_16x16x32_bf16 v[122:125], v[154:157], v[178:181], v[122:125]
	v_mfma_f32_16x16x32_bf16 v[118:121], v[146:149], v[186:189], v[118:121]
	v_mfma_f32_16x16x32_bf16 v[114:117], v[154:157], v[186:189], v[114:117]
	v_mfma_f32_16x16x32_bf16 v[106:109], v[146:149], v[194:197], v[106:109]
	v_mfma_f32_16x16x32_bf16 v[98:101], v[154:157], v[194:197], v[98:101]
	v_mfma_f32_16x16x32_bf16 v[82:85], v[146:149], v[202:205], v[82:85]
	v_mfma_f32_16x16x32_bf16 v[74:77], v[154:157], v[202:205], v[74:77]
	v_mfma_f32_16x16x32_bf16 v[126:129], v[150:153], v[182:185], v[126:129]
	v_mfma_f32_16x16x32_bf16 v[122:125], v[158:161], v[182:185], v[122:125]
	v_mfma_f32_16x16x32_bf16 v[118:121], v[150:153], v[190:193], v[118:121]
	v_mfma_f32_16x16x32_bf16 v[114:117], v[158:161], v[190:193], v[114:117]
	v_mfma_f32_16x16x32_bf16 v[106:109], v[150:153], v[198:201], v[106:109]
	v_mfma_f32_16x16x32_bf16 v[98:101], v[158:161], v[198:201], v[98:101]
	v_mfma_f32_16x16x32_bf16 v[82:85], v[150:153], v[206:209], v[82:85]
	v_mfma_f32_16x16x32_bf16 v[74:77], v[158:161], v[206:209], v[74:77]
	v_mfma_f32_16x16x32_bf16 v[110:113], v[162:165], v[178:181], v[110:113]
	v_mfma_f32_16x16x32_bf16 v[102:105], v[170:173], v[178:181], v[102:105]
	v_mfma_f32_16x16x32_bf16 v[94:97], v[162:165], v[186:189], v[94:97]
	v_mfma_f32_16x16x32_bf16 v[90:93], v[170:173], v[186:189], v[90:93]
	v_mfma_f32_16x16x32_bf16 v[86:89], v[162:165], v[194:197], v[86:89]
	v_mfma_f32_16x16x32_bf16 v[78:81], v[170:173], v[194:197], v[78:81]
	v_mfma_f32_16x16x32_bf16 v[70:73], v[162:165], v[202:205], v[70:73]
	v_mfma_f32_16x16x32_bf16 v[66:69], v[170:173], v[202:205], v[66:69]
	v_mfma_f32_16x16x32_bf16 v[110:113], v[166:169], v[182:185], v[110:113]
	v_mfma_f32_16x16x32_bf16 v[102:105], v[174:177], v[182:185], v[102:105]
	v_mfma_f32_16x16x32_bf16 v[94:97], v[166:169], v[190:193], v[94:97]
	v_mfma_f32_16x16x32_bf16 v[90:93], v[174:177], v[190:193], v[90:93]
	v_mfma_f32_16x16x32_bf16 v[86:89], v[166:169], v[198:201], v[86:89]
	v_mfma_f32_16x16x32_bf16 v[78:81], v[174:177], v[198:201], v[78:81]
	v_mfma_f32_16x16x32_bf16 v[70:73], v[166:169], v[206:209], v[70:73]
	v_mfma_f32_16x16x32_bf16 v[66:69], v[174:177], v[206:209], v[66:69]
	s_barrier
	s_mov_b32 m0, s35
	v_lshl_add_u64 v[210:211], v[210:211], 0, s[2:3]
	s_add_u32 s14, s14, 0x40080
	ds_read_b128 v[178:181], v142 offset:49152
	ds_read_b128 v[182:185], v142 offset:50176
	ds_read_b128 v[186:189], v142 offset:51200
	ds_read_b128 v[190:193], v142 offset:52224
	ds_read_b128 v[194:197], v142 offset:53248
	ds_read_b128 v[198:201], v142 offset:54272
	ds_read_b128 v[202:205], v142 offset:55296
	ds_read_b128 v[206:209], v142 offset:56320
	global_load_lds_dwordx4 v[210:211], off
	v_lshl_add_u64 v[210:211], v[212:213], 0, s[2:3]
	s_mov_b32 m0, s36
	s_addc_u32 s15, s15, 0
	global_load_lds_dwordx4 v[210:211], off
	s_mov_b32 m0, s37
	s_nop 0
	global_load_lds_dwordx4 v130, s[14:15]
	s_mov_b32 m0, s38
	s_nop 0
	global_load_lds_dwordx4 v132, s[14:15]
	v_lshl_add_u64 v[210:211], v[214:215], 0, s[2:3]
	s_mov_b32 m0, s24
	s_nop 0
	global_load_lds_dwordx4 v[210:211], off
	v_lshl_add_u64 v[210:211], v[216:217], 0, s[2:3]
	s_mov_b32 m0, s25
	s_nop 0
	global_load_lds_dwordx4 v[210:211], off
	s_waitcnt vmcnt(8)
	s_waitcnt lgkmcnt(0)
	s_barrier
	s_waitcnt lgkmcnt(0)
	v_mfma_f32_16x16x32_bf16 v[62:65], v[146:149], v[178:181], v[62:65]
	v_mfma_f32_16x16x32_bf16 v[58:61], v[154:157], v[178:181], v[58:61]
	v_mfma_f32_16x16x32_bf16 v[54:57], v[146:149], v[186:189], v[54:57]
	v_mfma_f32_16x16x32_bf16 v[50:53], v[154:157], v[186:189], v[50:53]
	v_mfma_f32_16x16x32_bf16 v[34:37], v[146:149], v[194:197], v[34:37]
	v_mfma_f32_16x16x32_bf16 v[26:29], v[154:157], v[194:197], v[26:29]
	v_mfma_f32_16x16x32_bf16 v[22:25], v[146:149], v[202:205], v[22:25]
	v_mfma_f32_16x16x32_bf16 v[10:13], v[154:157], v[202:205], v[10:13]
	v_mfma_f32_16x16x32_bf16 v[62:65], v[150:153], v[182:185], v[62:65]
	v_mfma_f32_16x16x32_bf16 v[58:61], v[158:161], v[182:185], v[58:61]
	v_mfma_f32_16x16x32_bf16 v[54:57], v[150:153], v[190:193], v[54:57]
	v_mfma_f32_16x16x32_bf16 v[50:53], v[158:161], v[190:193], v[50:53]
	v_mfma_f32_16x16x32_bf16 v[34:37], v[150:153], v[198:201], v[34:37]
	v_mfma_f32_16x16x32_bf16 v[26:29], v[158:161], v[198:201], v[26:29]
	v_mfma_f32_16x16x32_bf16 v[22:25], v[150:153], v[206:209], v[22:25]
	v_mfma_f32_16x16x32_bf16 v[10:13], v[158:161], v[206:209], v[10:13]
	v_mfma_f32_16x16x32_bf16 v[46:49], v[162:165], v[178:181], v[46:49]
	v_mfma_f32_16x16x32_bf16 v[42:45], v[170:173], v[178:181], v[42:45]
	v_mfma_f32_16x16x32_bf16 v[38:41], v[162:165], v[186:189], v[38:41]
	v_mfma_f32_16x16x32_bf16 v[30:33], v[170:173], v[186:189], v[30:33]
	v_mfma_f32_16x16x32_bf16 v[18:21], v[162:165], v[194:197], v[18:21]
	v_mfma_f32_16x16x32_bf16 v[14:17], v[170:173], v[194:197], v[14:17]
	v_mfma_f32_16x16x32_bf16 v[6:9], v[162:165], v[202:205], v[6:9]
	v_mfma_f32_16x16x32_bf16 v[2:5], v[170:173], v[202:205], v[2:5]
	v_mfma_f32_16x16x32_bf16 v[46:49], v[166:169], v[182:185], v[46:49]
	v_mfma_f32_16x16x32_bf16 v[42:45], v[174:177], v[182:185], v[42:45]
	v_mfma_f32_16x16x32_bf16 v[38:41], v[166:169], v[190:193], v[38:41]
	v_mfma_f32_16x16x32_bf16 v[30:33], v[174:177], v[190:193], v[30:33]
	v_mfma_f32_16x16x32_bf16 v[18:21], v[166:169], v[198:201], v[18:21]
	v_mfma_f32_16x16x32_bf16 v[14:17], v[174:177], v[198:201], v[14:17]
	v_mfma_f32_16x16x32_bf16 v[6:9], v[166:169], v[206:209], v[6:9]
	v_mfma_f32_16x16x32_bf16 v[2:5], v[174:177], v[206:209], v[2:5]
	s_barrier
	s_add_i32 s27, s27, 2
	s_add_u32 s12, s12, 0x100
	s_addc_u32 s13, s13, 0
	s_cmp_gt_u32 s27, 13
	s_cbranch_scc0 .LBB0_1250
	s_cmpk_lt_u32 s19, 0x100
	s_cbranch_scc0 .LBB0_1253
	s_barrier

.LBB0_1381:
	ds_read_b128 v[138:141], v147
	ds_read_b128 v[150:153], v147 offset:1024
	ds_read_b128 v[154:157], v147 offset:2048
	ds_read_b128 v[158:161], v147 offset:3072
	ds_read_b128 v[162:165], v148
	ds_read_b128 v[166:169], v148 offset:1024
	ds_read_b128 v[170:173], v148 offset:2048
	ds_read_b128 v[174:177], v148 offset:3072
	s_add_u32 s24, s2, 0xfffc0080
	s_addc_u32 s25, s3, -1
	s_cmp_eq_u32 s53, 12
	s_cselect_b32 s27, s17, s25
	s_cselect_b32 s26, s49, s24
	s_cselect_b32 s25, s15, s52
	s_cselect_b32 s24, s50, s51
	s_add_i32 m0, s23, 0xc000
	ds_read_b128 v[178:181], v149
	ds_read_b128 v[182:185], v149 offset:1024
	ds_read_b128 v[186:189], v149 offset:2048
	ds_read_b128 v[190:193], v149 offset:3072
	ds_read_b128 v[194:197], v149 offset:4096
	ds_read_b128 v[198:201], v149 offset:5120
	ds_read_b128 v[202:205], v149 offset:6144
	ds_read_b128 v[206:209], v149 offset:7168
	global_load_lds_dwordx4 v132, s[2:3]
	s_add_i32 m0, s23, 0xe000
	s_nop 0
	global_load_lds_dwordx4 v134, s[2:3]
	s_waitcnt vmcnt(8)
	s_waitcnt lgkmcnt(0)
	s_barrier
	s_waitcnt lgkmcnt(0)
	v_mfma_f32_16x16x32_bf16 v[124:127], v[138:141], v[178:181], v[124:127]
	v_mfma_f32_16x16x32_bf16 v[120:123], v[154:157], v[178:181], v[120:123]
	v_mfma_f32_16x16x32_bf16 v[116:119], v[138:141], v[186:189], v[116:119]
	v_mfma_f32_16x16x32_bf16 v[112:115], v[154:157], v[186:189], v[112:115]
	v_mfma_f32_16x16x32_bf16 v[104:107], v[138:141], v[194:197], v[104:107]
	v_mfma_f32_16x16x32_bf16 v[96:99], v[154:157], v[194:197], v[96:99]
	v_mfma_f32_16x16x32_bf16 v[88:91], v[138:141], v[202:205], v[88:91]
	v_mfma_f32_16x16x32_bf16 v[80:83], v[154:157], v[202:205], v[80:83]
	v_mfma_f32_16x16x32_bf16 v[124:127], v[150:153], v[182:185], v[124:127]
	v_mfma_f32_16x16x32_bf16 v[120:123], v[158:161], v[182:185], v[120:123]
	v_mfma_f32_16x16x32_bf16 v[116:119], v[150:153], v[190:193], v[116:119]
	v_mfma_f32_16x16x32_bf16 v[112:115], v[158:161], v[190:193], v[112:115]
	v_mfma_f32_16x16x32_bf16 v[104:107], v[150:153], v[198:201], v[104:107]
	v_mfma_f32_16x16x32_bf16 v[96:99], v[158:161], v[198:201], v[96:99]
	v_mfma_f32_16x16x32_bf16 v[88:91], v[150:153], v[206:209], v[88:91]
	v_mfma_f32_16x16x32_bf16 v[80:83], v[158:161], v[206:209], v[80:83]
	v_mfma_f32_16x16x32_bf16 v[108:111], v[162:165], v[178:181], v[108:111]
	v_mfma_f32_16x16x32_bf16 v[100:103], v[170:173], v[178:181], v[100:103]
	v_mfma_f32_16x16x32_bf16 v[92:95], v[162:165], v[186:189], v[92:95]
	v_mfma_f32_16x16x32_bf16 v[84:87], v[170:173], v[186:189], v[84:87]
	v_mfma_f32_16x16x32_bf16 v[76:79], v[162:165], v[194:197], v[76:79]
	v_mfma_f32_16x16x32_bf16 v[72:75], v[170:173], v[194:197], v[72:75]
	v_mfma_f32_16x16x32_bf16 v[68:71], v[162:165], v[202:205], v[68:71]
	v_mfma_f32_16x16x32_bf16 v[64:67], v[170:173], v[202:205], v[64:67]
	v_mfma_f32_16x16x32_bf16 v[108:111], v[166:169], v[182:185], v[108:111]
	v_mfma_f32_16x16x32_bf16 v[100:103], v[174:177], v[182:185], v[100:103]
	v_mfma_f32_16x16x32_bf16 v[92:95], v[166:169], v[190:193], v[92:95]
	v_mfma_f32_16x16x32_bf16 v[84:87], v[174:177], v[190:193], v[84:87]
	v_mfma_f32_16x16x32_bf16 v[76:79], v[166:169], v[198:201], v[76:79]
	v_mfma_f32_16x16x32_bf16 v[72:75], v[174:177], v[198:201], v[72:75]
	v_mfma_f32_16x16x32_bf16 v[68:71], v[166:169], v[206:209], v[68:71]
	v_mfma_f32_16x16x32_bf16 v[64:67], v[174:177], v[206:209], v[64:67]
	s_barrier
	s_add_i32 s54, s4, s29
	s_mov_b32 m0, s54
	ds_read_b128 v[178:181], v149 offset:16384
	ds_read_b128 v[182:185], v149 offset:17408
	ds_read_b128 v[186:189], v149 offset:18432
	ds_read_b128 v[190:193], v149 offset:19456
	ds_read_b128 v[194:197], v149 offset:20480
	ds_read_b128 v[198:201], v149 offset:21504
	ds_read_b128 v[202:205], v149 offset:22528
	ds_read_b128 v[206:209], v149 offset:23552
	global_load_lds_dwordx4 v130, s[24:25]
	s_add_i32 m0, s54, 0x2000
	s_add_u32 s54, s24, 0x40000
	s_addc_u32 s55, s25, 0
	s_add_i32 s56, s41, s29
	global_load_lds_dwordx4 v128, s[24:25]
	s_mov_b32 m0, s56
	v_lshl_add_u64 v[214:215], s[26:27], 0, v[128:129]
	global_load_lds_dwordx4 v130, s[54:55]
	s_add_i32 m0, s56, 0x2000
	s_nop 0
	global_load_lds_dwordx4 v128, s[54:55]
	v_lshl_add_u64 v[212:213], s[26:27], 0, v[130:131]
	s_mov_b32 m0, s23
	s_nop 0
	global_load_lds_dwordx4 v130, s[26:27]
	s_mov_b32 m0, s34
	s_nop 0
	global_load_lds_dwordx4 v128, s[26:27]
	s_waitcnt vmcnt(8)
	s_waitcnt lgkmcnt(0)
	s_barrier
	s_waitcnt lgkmcnt(0)
	v_mfma_f32_16x16x32_bf16 v[60:63], v[138:141], v[178:181], v[60:63]
	v_mfma_f32_16x16x32_bf16 v[56:59], v[154:157], v[178:181], v[56:59]
	v_mfma_f32_16x16x32_bf16 v[52:55], v[138:141], v[186:189], v[52:55]
	v_mfma_f32_16x16x32_bf16 v[48:51], v[154:157], v[186:189], v[48:51]
	v_mfma_f32_16x16x32_bf16 v[44:47], v[138:141], v[194:197], v[44:47]
	v_mfma_f32_16x16x32_bf16 v[32:35], v[154:157], v[194:197], v[32:35]
	v_mfma_f32_16x16x32_bf16 v[20:23], v[138:141], v[202:205], v[20:23]
	v_mfma_f32_16x16x32_bf16 v[8:11], v[154:157], v[202:205], v[8:11]
	v_mfma_f32_16x16x32_bf16 v[60:63], v[150:153], v[182:185], v[60:63]
	v_mfma_f32_16x16x32_bf16 v[56:59], v[158:161], v[182:185], v[56:59]
	v_mfma_f32_16x16x32_bf16 v[52:55], v[150:153], v[190:193], v[52:55]
	v_mfma_f32_16x16x32_bf16 v[48:51], v[158:161], v[190:193], v[48:51]
	v_mfma_f32_16x16x32_bf16 v[44:47], v[150:153], v[198:201], v[44:47]
	v_mfma_f32_16x16x32_bf16 v[32:35], v[158:161], v[198:201], v[32:35]
	v_mfma_f32_16x16x32_bf16 v[20:23], v[150:153], v[206:209], v[20:23]
	v_mfma_f32_16x16x32_bf16 v[8:11], v[158:161], v[206:209], v[8:11]
	v_mfma_f32_16x16x32_bf16 v[40:43], v[162:165], v[178:181], v[40:43]
	v_mfma_f32_16x16x32_bf16 v[36:39], v[170:173], v[178:181], v[36:39]
	v_mfma_f32_16x16x32_bf16 v[28:31], v[162:165], v[186:189], v[28:31]
	v_mfma_f32_16x16x32_bf16 v[24:27], v[170:173], v[186:189], v[24:27]
	v_mfma_f32_16x16x32_bf16 v[16:19], v[162:165], v[194:197], v[16:19]
	v_mfma_f32_16x16x32_bf16 v[12:15], v[170:173], v[194:197], v[12:15]
	v_mfma_f32_16x16x32_bf16 v[4:7], v[162:165], v[202:205], v[4:7]
	v_mfma_f32_16x16x32_bf16 v[0:3], v[170:173], v[202:205], v[0:3]
	v_mfma_f32_16x16x32_bf16 v[40:43], v[166:169], v[182:185], v[40:43]
	v_mfma_f32_16x16x32_bf16 v[36:39], v[174:177], v[182:185], v[36:39]
	v_mfma_f32_16x16x32_bf16 v[28:31], v[166:169], v[190:193], v[28:31]
	v_mfma_f32_16x16x32_bf16 v[24:27], v[174:177], v[190:193], v[24:27]
	v_mfma_f32_16x16x32_bf16 v[16:19], v[166:169], v[198:201], v[16:19]
	v_mfma_f32_16x16x32_bf16 v[12:15], v[174:177], v[198:201], v[12:15]
	v_mfma_f32_16x16x32_bf16 v[4:7], v[166:169], v[206:209], v[4:7]
	v_mfma_f32_16x16x32_bf16 v[0:3], v[174:177], v[206:209], v[0:3]
	s_barrier
	s_add_i32 s54, 0, 0x18000
	s_add_i32 s55, 0, 0x1c000
	v_add_u32_e32 v158, s54, v145
	v_add_u32_e32 v174, s55, v145
	ds_read_b128 v[138:141], v158
	ds_read_b128 v[150:153], v158 offset:1024
	ds_read_b128 v[154:157], v158 offset:2048
	ds_read_b128 v[158:161], v158 offset:3072
	ds_read_b128 v[162:165], v174
	ds_read_b128 v[166:169], v174 offset:1024
	ds_read_b128 v[170:173], v174 offset:2048
	ds_read_b128 v[174:177], v174 offset:3072
	s_add_u32 s26, s26, 0x40000
	s_addc_u32 s27, s27, 0
	s_mov_b32 m0, s35
	ds_read_b128 v[178:181], v149 offset:32768
	ds_read_b128 v[182:185], v149 offset:33792
	ds_read_b128 v[186:189], v149 offset:34816
	ds_read_b128 v[190:193], v149 offset:35840
	ds_read_b128 v[194:197], v149 offset:36864
	ds_read_b128 v[198:201], v149 offset:37888
	ds_read_b128 v[202:205], v149 offset:38912
	ds_read_b128 v[206:209], v149 offset:39936
	global_load_lds_dwordx4 v130, s[26:27]
	s_mov_b32 m0, s36
	s_nop 0
	global_load_lds_dwordx4 v128, s[26:27]
	s_waitcnt vmcnt(8)
	s_waitcnt lgkmcnt(0)
	s_barrier
	s_waitcnt lgkmcnt(0)
	v_mfma_f32_16x16x32_bf16 v[124:127], v[138:141], v[178:181], v[124:127]
	v_mfma_f32_16x16x32_bf16 v[120:123], v[154:157], v[178:181], v[120:123]
	v_mfma_f32_16x16x32_bf16 v[116:119], v[138:141], v[186:189], v[116:119]
	v_mfma_f32_16x16x32_bf16 v[112:115], v[154:157], v[186:189], v[112:115]
	v_mfma_f32_16x16x32_bf16 v[104:107], v[138:141], v[194:197], v[104:107]
	v_mfma_f32_16x16x32_bf16 v[96:99], v[154:157], v[194:197], v[96:99]
	v_mfma_f32_16x16x32_bf16 v[88:91], v[138:141], v[202:205], v[88:91]
	v_mfma_f32_16x16x32_bf16 v[80:83], v[154:157], v[202:205], v[80:83]
	v_mfma_f32_16x16x32_bf16 v[124:127], v[150:153], v[182:185], v[124:127]
	v_mfma_f32_16x16x32_bf16 v[120:123], v[158:161], v[182:185], v[120:123]
	v_mfma_f32_16x16x32_bf16 v[116:119], v[150:153], v[190:193], v[116:119]
	v_mfma_f32_16x16x32_bf16 v[112:115], v[158:161], v[190:193], v[112:115]
	v_mfma_f32_16x16x32_bf16 v[104:107], v[150:153], v[198:201], v[104:107]
	v_mfma_f32_16x16x32_bf16 v[96:99], v[158:161], v[198:201], v[96:99]
	v_mfma_f32_16x16x32_bf16 v[88:91], v[150:153], v[206:209], v[88:91]
	v_mfma_f32_16x16x32_bf16 v[80:83], v[158:161], v[206:209], v[80:83]
	v_mfma_f32_16x16x32_bf16 v[108:111], v[162:165], v[178:181], v[108:111]
	v_mfma_f32_16x16x32_bf16 v[100:103], v[170:173], v[178:181], v[100:103]
	v_mfma_f32_16x16x32_bf16 v[92:95], v[162:165], v[186:189], v[92:95]
	v_mfma_f32_16x16x32_bf16 v[84:87], v[170:173], v[186:189], v[84:87]
	v_mfma_f32_16x16x32_bf16 v[76:79], v[162:165], v[194:197], v[76:79]
	v_mfma_f32_16x16x32_bf16 v[72:75], v[170:173], v[194:197], v[72:75]
	v_mfma_f32_16x16x32_bf16 v[68:71], v[162:165], v[202:205], v[68:71]
	v_mfma_f32_16x16x32_bf16 v[64:67], v[170:173], v[202:205], v[64:67]
	v_mfma_f32_16x16x32_bf16 v[108:111], v[166:169], v[182:185], v[108:111]
	v_mfma_f32_16x16x32_bf16 v[100:103], v[174:177], v[182:185], v[100:103]
	v_mfma_f32_16x16x32_bf16 v[92:95], v[166:169], v[190:193], v[92:95]
	v_mfma_f32_16x16x32_bf16 v[84:87], v[174:177], v[190:193], v[84:87]
	v_mfma_f32_16x16x32_bf16 v[76:79], v[166:169], v[198:201], v[76:79]
	v_mfma_f32_16x16x32_bf16 v[72:75], v[174:177], v[198:201], v[72:75]
	v_mfma_f32_16x16x32_bf16 v[68:71], v[166:169], v[206:209], v[68:71]
	v_mfma_f32_16x16x32_bf16 v[64:67], v[174:177], v[206:209], v[64:67]
	s_barrier
	s_add_i32 s26, s54, s29
	s_add_i32 m0, s26, 0xffffff80
	ds_read_b128 v[178:181], v149 offset:49152
	ds_read_b128 v[182:185], v149 offset:50176
	ds_read_b128 v[186:189], v149 offset:51200
	ds_read_b128 v[190:193], v149 offset:52224
	ds_read_b128 v[194:197], v149 offset:53248
	ds_read_b128 v[198:201], v149 offset:54272
	ds_read_b128 v[202:205], v149 offset:55296
	ds_read_b128 v[206:209], v149 offset:56320
	global_load_lds_dwordx4 v130, s[24:25] offset:128
	s_add_i32 m0, s26, 0x1f80
	s_add_i32 s26, s55, s29
	global_load_lds_dwordx4 v128, s[24:25] offset:128
	s_add_u32 s24, s24, 0x40080
	s_addc_u32 s25, s25, 0
	s_mov_b32 m0, s26
	s_nop 0
	global_load_lds_dwordx4 v130, s[24:25]
	s_add_i32 m0, s26, 0x2000
	s_nop 0
	global_load_lds_dwordx4 v128, s[24:25]
	v_lshl_add_u64 v[142:143], v[212:213], 0, s[8:9]
	s_mov_b32 m0, s38
	s_nop 0
	global_load_lds_dwordx4 v[142:143], off
	v_lshl_add_u64 v[142:143], v[214:215], 0, s[8:9]
	s_mov_b32 m0, s39
	s_nop 0
	global_load_lds_dwordx4 v[142:143], off
	s_waitcnt vmcnt(8)
	s_waitcnt lgkmcnt(0)
	s_barrier
	s_waitcnt lgkmcnt(0)
	v_mfma_f32_16x16x32_bf16 v[60:63], v[138:141], v[178:181], v[60:63]
	v_mfma_f32_16x16x32_bf16 v[56:59], v[154:157], v[178:181], v[56:59]
	v_mfma_f32_16x16x32_bf16 v[52:55], v[138:141], v[186:189], v[52:55]
	v_mfma_f32_16x16x32_bf16 v[48:51], v[154:157], v[186:189], v[48:51]
	v_mfma_f32_16x16x32_bf16 v[44:47], v[138:141], v[194:197], v[44:47]
	v_mfma_f32_16x16x32_bf16 v[32:35], v[154:157], v[194:197], v[32:35]
	v_mfma_f32_16x16x32_bf16 v[20:23], v[138:141], v[202:205], v[20:23]
	v_mfma_f32_16x16x32_bf16 v[8:11], v[154:157], v[202:205], v[8:11]
	v_mfma_f32_16x16x32_bf16 v[60:63], v[150:153], v[182:185], v[60:63]
	v_mfma_f32_16x16x32_bf16 v[56:59], v[158:161], v[182:185], v[56:59]
	v_mfma_f32_16x16x32_bf16 v[52:55], v[150:153], v[190:193], v[52:55]
	v_mfma_f32_16x16x32_bf16 v[48:51], v[158:161], v[190:193], v[48:51]
	v_mfma_f32_16x16x32_bf16 v[44:47], v[150:153], v[198:201], v[44:47]
	v_mfma_f32_16x16x32_bf16 v[32:35], v[158:161], v[198:201], v[32:35]
	v_mfma_f32_16x16x32_bf16 v[20:23], v[150:153], v[206:209], v[20:23]
	v_mfma_f32_16x16x32_bf16 v[8:11], v[158:161], v[206:209], v[8:11]
	v_mfma_f32_16x16x32_bf16 v[40:43], v[162:165], v[178:181], v[40:43]
	v_mfma_f32_16x16x32_bf16 v[36:39], v[170:173], v[178:181], v[36:39]
	v_mfma_f32_16x16x32_bf16 v[28:31], v[162:165], v[186:189], v[28:31]
	v_mfma_f32_16x16x32_bf16 v[24:27], v[170:173], v[186:189], v[24:27]
	v_mfma_f32_16x16x32_bf16 v[16:19], v[162:165], v[194:197], v[16:19]
	v_mfma_f32_16x16x32_bf16 v[12:15], v[170:173], v[194:197], v[12:15]
	v_mfma_f32_16x16x32_bf16 v[4:7], v[162:165], v[202:205], v[4:7]
	v_mfma_f32_16x16x32_bf16 v[0:3], v[170:173], v[202:205], v[0:3]
	v_mfma_f32_16x16x32_bf16 v[40:43], v[166:169], v[182:185], v[40:43]
	v_mfma_f32_16x16x32_bf16 v[36:39], v[174:177], v[182:185], v[36:39]
	v_mfma_f32_16x16x32_bf16 v[28:31], v[166:169], v[190:193], v[28:31]
	v_mfma_f32_16x16x32_bf16 v[24:27], v[174:177], v[190:193], v[24:27]
	v_mfma_f32_16x16x32_bf16 v[16:19], v[166:169], v[198:201], v[16:19]
	v_mfma_f32_16x16x32_bf16 v[12:15], v[174:177], v[198:201], v[12:15]
	v_mfma_f32_16x16x32_bf16 v[4:7], v[166:169], v[206:209], v[4:7]
	v_mfma_f32_16x16x32_bf16 v[0:3], v[174:177], v[206:209], v[0:3]
	s_barrier
	s_add_i32 s53, s53, 2
	s_add_u32 s2, s2, 0x100
	s_addc_u32 s3, s3, 0
	s_add_u32 s51, s51, 0x100
	s_addc_u32 s52, s52, 0
	s_cmp_gt_u32 s53, 13
	s_cbranch_scc0 .LBB0_1381
	s_and_b64 vcc, exec, s[10:11]
	s_cbranch_vccz .LBB0_1384
	s_barrier
